# light grid barriers (no L2 write-back) on XCD-local phase boundaries, guarded by a run-time placement census
# speedup vs baseline: 1.0519x; 1.0015x over previous
.LBB0_2:
	s_or_b64 exec, exec, s[2:3]
	s_load_dwordx2 s[34:35], s[0:1], 0x170
	s_load_dword s29, s[0:1], 0x178
	s_waitcnt lgkmcnt(0)
	s_barrier
	s_getreg_b32 s2, hwreg(HW_REG_XCC_ID, 0, 4)
	s_and_b32 s28, s2, 15
	s_mov_b64 s[2:3], exec
	v_readlane_b32 s6, v253, 1
	v_readlane_b32 s7, v253, 2
	s_and_b64 s[6:7], s[2:3], s[6:7]
	s_mov_b64 exec, s[6:7]
	s_cbranch_execz .LBB0_5
	s_mov_b64 s[6:7], exec
	v_mbcnt_lo_u32_b32 v1, s6, 0
	v_mbcnt_hi_u32_b32 v1, s7, v1
	v_cmp_eq_u32_e32 vcc, 0, v1
	s_and_b64 s[8:9], exec, vcc
	s_mov_b64 exec, s[8:9]
	s_cbranch_execz .LBB0_5
	s_lshl_b32 s8, s28, 8
	s_bcnt1_i32_b64 s6, s[6:7]
	v_mov_b32_e32 v1, s8
	v_mov_b32_e32 v2, s6
	global_atomic_add v1, v2, s[30:31] offset:1024
	v_readlane_b32 s8, v253, 0
	s_nop 3
	s_and_b32 s8, s8, 7
	s_lshl_b32 s8, s8, 8
	s_add_u32 s8, s8, 0x2400
	s_lshl_b32 s6, 1, s28
	v_mov_b32_e32 v1, s8
	v_mov_b32_e32 v2, s6
	s_nop 1
	global_atomic_or v2, v1, v2, s[30:31] sc0
	s_waitcnt vmcnt(0)

.Lxb_have_census:
	v_readlane_b32 s28, v253, 61
	v_readlane_b32 s29, v253, 62
	v_readlane_b32 s38, v254, 1
	v_readlane_b32 s39, v254, 2
	v_mov_b32_e32 v3, 1
	s_mul_i32 s2, s2, s37
	s_mul_i32 s3, s3, s37
	s_nop 4
	global_atomic_add v3, v201, v3, s[28:29] sc0
	buffer_inv sc1
	s_waitcnt vmcnt(0)
	v_readfirstlane_b32 s28, v3
	s_nop 3
	s_add_u32 s28, s28, 1
	s_cmp_eq_u32 s28, s2
	s_cbranch_scc0 .Lxb_poll
	s_cmp_eq_u32 s74, 6
	s_cbranch_scc1 .Lxb_maybe_light
	s_cmp_eq_u32 s74, 12
	s_cbranch_scc1 .Lxb_maybe_light
	s_cmp_eq_u32 s74, 13
	s_cbranch_scc1 .Lxb_maybe_light
	s_branch .Lxb_flush
.Lxb_maybe_light:
	ds_read_b32 v4, v208 offset:8
	s_waitcnt lgkmcnt(0)
	v_readfirstlane_b32 s28, v4
	s_nop 3
	s_cmp_eq_u32 s28, 1
	s_cbranch_scc1 .Lxb_noflush
.Lxb_flush:
	buffer_wbl2 sc1
	s_waitcnt vmcnt(0)
.Lxb_noflush:
	global_atomic_add v201, v249, s[38:39]

.Lxb_done:
	s_cmp_eq_u32 s37, 1
	s_cbranch_scc0 .Lxb_nochk
	s_mov_b64 exec, 0xff
	v_lshlrev_b32_e32 v4, 8, v237
	v_add_u32_e32 v4, 0x2400, v4
	global_load_dword v5, v4, s[88:89] sc1
	s_waitcnt vmcnt(0)
	v_add_u32_e32 v6, -1, v5
	v_and_b32_e32 v6, v6, v5
	v_cmp_ne_u32_e32 vcc, 0, v6
	s_nop 3
	s_and_b64 s[28:29], vcc, exec
	s_and_b32 s2, s68, 7
	s_or_b32 s28, s28, s29
	s_or_b32 s28, s28, s2
	s_cmp_eq_u32 s28, 0
	s_cselect_b32 s28, 1, 0
	s_mov_b64 exec, 1
	v_mov_b32_e32 v4, s28
	ds_write_b32 v208, v4 offset:8
	s_waitcnt lgkmcnt(0)
